# v5 + NA attention QK^T K-fragment reads software-pipelined 6 deep through spare VGPRs (v208-v231); bit-identical
# speedup vs baseline: 1.0066x; 1.0010x over previous
; #define ALAS __attribute__((address_space(3)))
; __device__ __forceinline__ void qkt(f32x16& p0, f32x16& p1, const ALAS char* Ks, const bf16x8* qr, int r32, int hi) {
;   p0 = f32x16{}; p1 = f32x16{};
; #pragma unroll
;   for (int d0 = 0; d0 < 8; ++d0) { int cb = (d0 * 16 + hi * 8) * 2;
;     bf16x8 b0 = *(const ALAS bf16x8*)(Ks + KSWZ(r32, cb));
;     bf16x8 b1 = *(const ALAS bf16x8*)(Ks + KSWZ(32 + r32, cb));
;     p0 = __builtin_amdgcn_mfma_f32_32x32x16_bf16(b0, qr[d0], p0, 0, 0, 0);
;     p1 = __builtin_amdgcn_mfma_f32_32x32x16_bf16(b1, qr[d0], p1, 0, 0, 0); }
; }
; template <int MODE> __device__ __forceinline__ void modify(f32x16& p0, f32x16& p1, const Mod& M, int j, float& boff) {
;     ...
;       const int base = (kr - M.rq + 7) * 31 + 15 - M.c + 4 * M.hi; const int d0 = 4 * M.hi - M.cs;
; #pragma unroll
;       for (int r = 0; r < 16; ++r) { const int cr = (r & 3) + 8 * (r >> 2);
;         const bool v0 = (unsigned)(cr + d0) < 16u, v1 = (unsigned)(cr + 32 + d0) < 16u;
;         const float b0 = M.tab[v0 ? base + cr : 0], b1 = M.tab[v1 ? base + cr + 32 : 0];
;         p0[r] = v0 ? p0[r] + b0 : NEG; p1[r] = v1 ? p1[r] + b1 : NEG; }
.LBB0_385:
	s_add_i32 s8, s16, s45
	v_cmp_ge_i32_e32 vcc, s8, v139
	v_cmp_lt_i32_e64 s[6:7], s8, v141
	s_and_b64 s[6:7], vcc, s[6:7]
	s_andn2_b64 vcc, exec, s[6:7]
	s_cbranch_vccnz .LBB0_424
	s_and_b32 s90, s16, 1
	v_mov_b32_e32 v64, v137
	v_mov_b32_e32 v65, v136
	s_lshl_b32 s6, s90, 14
	s_add_i32 s6, s6, 0
	s_add_i32 s6, s6, 0x10000
	v_lshlrev_b32_e32 v149, 4, v64
	v_lshlrev_b32_e32 v158, 4, v65
	v_and_b32_e32 v158, 0x70, v158
	v_lshl_add_u32 v159, v65, 8, s6
	v_xad_u32 v150, v149, v158, v159
	v_add_u32_e32 v247, 32, v149
	v_xad_u32 v151, v247, v158, v159
	v_add_u32_e32 v247, 64, v149
	v_xad_u32 v152, v247, v158, v159
	v_add_u32_e32 v247, 0x60, v149
	v_xad_u32 v153, v247, v158, v159
	s_sub_i32 s6, s8, s88
	s_mul_i32 s6, s6, 31
	s_movk_i32 s8, 0xffe0
	ds_read_b128 v[208:211], v150
	ds_read_b128 v[212:215], v150 offset:8192
	ds_read_b128 v[216:219], v151
	ds_read_b128 v[220:223], v151 offset:8192
	ds_read_b128 v[224:227], v152
	ds_read_b128 v[228:231], v152 offset:8192
	s_waitcnt lgkmcnt(5)
	v_mfma_f32_32x32x16_bf16 v[80:95], v[208:211], v[96:99], 0
	ds_read_b128 v[208:211], v153
	s_waitcnt lgkmcnt(5)
	v_mfma_f32_32x32x16_bf16 v[64:79], v[212:215], v[96:99], 0
	ds_read_b128 v[212:215], v153 offset:8192
	s_waitcnt lgkmcnt(5)
	v_mfma_f32_32x32x16_bf16 v[80:95], v[216:219], v[100:103], v[80:95]
	ds_read_b128 v[216:219], v150 offset:128
	s_waitcnt lgkmcnt(5)
	v_mfma_f32_32x32x16_bf16 v[64:79], v[220:223], v[100:103], v[64:79]
	ds_read_b128 v[220:223], v150 offset:8320
	s_waitcnt lgkmcnt(5)
	v_mfma_f32_32x32x16_bf16 v[80:95], v[224:227], v[104:107], v[80:95]
	ds_read_b128 v[224:227], v151 offset:128
	s_waitcnt lgkmcnt(5)
	v_mfma_f32_32x32x16_bf16 v[64:79], v[228:231], v[104:107], v[64:79]
	ds_read_b128 v[228:231], v151 offset:8320
	s_waitcnt lgkmcnt(5)
	v_mfma_f32_32x32x16_bf16 v[80:95], v[208:211], v[108:111], v[80:95]
	ds_read_b128 v[208:211], v152 offset:128
	s_waitcnt lgkmcnt(5)
	v_mfma_f32_32x32x16_bf16 v[64:79], v[212:215], v[108:111], v[64:79]
	ds_read_b128 v[212:215], v152 offset:8320
	s_waitcnt lgkmcnt(5)
	v_mfma_f32_32x32x16_bf16 v[80:95], v[216:219], v[112:115], v[80:95]
	ds_read_b128 v[216:219], v153 offset:128
	s_waitcnt lgkmcnt(5)
	v_mfma_f32_32x32x16_bf16 v[64:79], v[220:223], v[112:115], v[64:79]
	ds_read_b128 v[220:223], v153 offset:8320
	s_waitcnt lgkmcnt(5)
	v_mfma_f32_32x32x16_bf16 v[80:95], v[224:227], v[116:119], v[80:95]
	s_waitcnt lgkmcnt(4)
	v_mfma_f32_32x32x16_bf16 v[64:79], v[228:231], v[116:119], v[64:79]
	s_waitcnt lgkmcnt(3)
	v_mfma_f32_32x32x16_bf16 v[80:95], v[208:211], v[120:123], v[80:95]
	s_waitcnt lgkmcnt(2)
	v_mfma_f32_32x32x16_bf16 v[64:79], v[212:215], v[120:123], v[64:79]
	s_waitcnt lgkmcnt(1)
	v_mfma_f32_32x32x16_bf16 v[80:95], v[216:219], v[124:127], v[80:95]
	s_waitcnt lgkmcnt(0)
	v_mfma_f32_32x32x16_bf16 v[64:79], v[220:223], v[124:127], v[64:79]
	v_mov_b32_e32 v149, v132
	v_mov_b32_e32 v150, v193
	v_mov_b32_e32 v151, v133
	s_nop 0
	v_lshlrev_b32_e32 v150, 2, v150
	v_sub_u32_e32 v149, s6, v149
	v_add_u32_e32 v149, v149, v150
	v_sub_u32_e32 v154, v150, v151
	v_and_b32_e32 v162, -16, v154
	v_add_u32_e32 v153, 0xe8, v149
	v_add_u32_e32 v149, 0x108, v149
	v_cmp_eq_u32_e32 vcc, s8, v162
	v_cmp_gt_u32_e64 s[6:7], 16, v154
	v_mov_b32_e32 v150, 0xff800000
	v_cndmask_b32_e32 v149, 0, v149, vcc
	v_lshl_add_u32 v149, v149, 2, 0
	v_add_u32_e32 v149, 0x18800, v149
	ds_read_b32 v152, v149
	v_mov_b32_e32 v149, 0xff800000
	s_and_saveexec_b64 s[8:9], s[6:7]
	s_cbranch_execz .LBB0_388
	v_lshl_add_u32 v150, v153, 2, 0
	v_add_u32_e32 v150, 0x18800, v150
	ds_read_b32 v150, v150
	s_waitcnt lgkmcnt(0)
	v_add_f32_e32 v150, v80, v150

; #define ALAS __attribute__((address_space(3)))
; __device__ __forceinline__ void qkt(f32x16& p0, f32x16& p1, const ALAS char* Ks, const bf16x8* qr, int r32, int hi) {
;   p0 = f32x16{}; p1 = f32x16{};
; #pragma unroll
;   for (int d0 = 0; d0 < 8; ++d0) { int cb = (d0 * 16 + hi * 8) * 2;
;     bf16x8 b0 = *(const ALAS bf16x8*)(Ks + KSWZ(r32, cb));
;     bf16x8 b1 = *(const ALAS bf16x8*)(Ks + KSWZ(32 + r32, cb));
;     p0 = __builtin_amdgcn_mfma_f32_32x32x16_bf16(b0, qr[d0], p0, 0, 0, 0);
;     p1 = __builtin_amdgcn_mfma_f32_32x32x16_bf16(b1, qr[d0], p1, 0, 0, 0); }
; }
; template <int MODE> __device__ __forceinline__ void modify(f32x16& p0, f32x16& p1, const Mod& M, int j, float& boff) {
;     ...
;       const int base = (kr - M.rq + 7) * 31 + 15 - M.c + 4 * M.hi; const int d0 = 4 * M.hi - M.cs;
; #pragma unroll
;       for (int r = 0; r < 16; ++r) { const int cr = (r & 3) + 8 * (r >> 2);
;         const bool v0 = (unsigned)(cr + d0) < 16u, v1 = (unsigned)(cr + 32 + d0) < 16u;
;         const float b0 = M.tab[v0 ? base + cr : 0], b1 = M.tab[v1 ? base + cr + 32 : 0];
;         p0[r] = v0 ? p0[r] + b0 : NEG; p1[r] = v1 ? p1[r] + b1 : NEG; }
.LBB0_1041:
	s_add_i32 s14, s20, s7
	v_cmp_ge_i32_e32 vcc, s14, v139
	v_cmp_lt_i32_e64 s[12:13], s14, v141
	s_and_b64 s[12:13], vcc, s[12:13]
	s_andn2_b64 vcc, exec, s[12:13]
	s_cbranch_vccnz .LBB0_1080
	s_and_b32 s88, s20, 1
	v_mov_b32_e32 v64, v137
	v_mov_b32_e32 v65, v136
	s_lshl_b32 s12, s88, 14
	s_add_i32 s12, s12, 0
	s_add_i32 s12, s12, 0x10000
	v_lshlrev_b32_e32 v149, 4, v64
	v_lshlrev_b32_e32 v158, 4, v65
	v_and_b32_e32 v158, 0x70, v158
	v_lshl_add_u32 v159, v65, 8, s12
	v_xad_u32 v150, v149, v158, v159
	v_add_u32_e32 v247, 32, v149
	v_xad_u32 v151, v247, v158, v159
	v_add_u32_e32 v247, 64, v149
	v_xad_u32 v152, v247, v158, v159
	v_add_u32_e32 v247, 0x60, v149
	v_xad_u32 v153, v247, v158, v159
	s_sub_i32 s12, s14, s86
	s_mul_i32 s12, s12, 31
	s_movk_i32 s14, 0xffe0
	ds_read_b128 v[208:211], v150
	ds_read_b128 v[212:215], v150 offset:8192
	ds_read_b128 v[216:219], v151
	ds_read_b128 v[220:223], v151 offset:8192
	ds_read_b128 v[224:227], v152
	ds_read_b128 v[228:231], v152 offset:8192
	s_waitcnt lgkmcnt(5)
	v_mfma_f32_32x32x16_bf16 v[80:95], v[208:211], v[96:99], 0
	ds_read_b128 v[208:211], v153
	s_waitcnt lgkmcnt(5)
	v_mfma_f32_32x32x16_bf16 v[64:79], v[212:215], v[96:99], 0
	ds_read_b128 v[212:215], v153 offset:8192
	s_waitcnt lgkmcnt(5)
	v_mfma_f32_32x32x16_bf16 v[80:95], v[216:219], v[100:103], v[80:95]
	ds_read_b128 v[216:219], v150 offset:128
	s_waitcnt lgkmcnt(5)
	v_mfma_f32_32x32x16_bf16 v[64:79], v[220:223], v[100:103], v[64:79]
	ds_read_b128 v[220:223], v150 offset:8320
	s_waitcnt lgkmcnt(5)
	v_mfma_f32_32x32x16_bf16 v[80:95], v[224:227], v[104:107], v[80:95]
	ds_read_b128 v[224:227], v151 offset:128
	s_waitcnt lgkmcnt(5)
	v_mfma_f32_32x32x16_bf16 v[64:79], v[228:231], v[104:107], v[64:79]
	ds_read_b128 v[228:231], v151 offset:8320
	s_waitcnt lgkmcnt(5)
	v_mfma_f32_32x32x16_bf16 v[80:95], v[208:211], v[108:111], v[80:95]
	ds_read_b128 v[208:211], v152 offset:128
	s_waitcnt lgkmcnt(5)
	v_mfma_f32_32x32x16_bf16 v[64:79], v[212:215], v[108:111], v[64:79]
	ds_read_b128 v[212:215], v152 offset:8320
	s_waitcnt lgkmcnt(5)
	v_mfma_f32_32x32x16_bf16 v[80:95], v[216:219], v[112:115], v[80:95]
	ds_read_b128 v[216:219], v153 offset:128
	s_waitcnt lgkmcnt(5)
	v_mfma_f32_32x32x16_bf16 v[64:79], v[220:223], v[112:115], v[64:79]
	ds_read_b128 v[220:223], v153 offset:8320
	s_waitcnt lgkmcnt(5)
	v_mfma_f32_32x32x16_bf16 v[80:95], v[224:227], v[116:119], v[80:95]
	s_waitcnt lgkmcnt(4)
	v_mfma_f32_32x32x16_bf16 v[64:79], v[228:231], v[116:119], v[64:79]
	s_waitcnt lgkmcnt(3)
	v_mfma_f32_32x32x16_bf16 v[80:95], v[208:211], v[120:123], v[80:95]
	s_waitcnt lgkmcnt(2)
	v_mfma_f32_32x32x16_bf16 v[64:79], v[212:215], v[120:123], v[64:79]
	s_waitcnt lgkmcnt(1)
	v_mfma_f32_32x32x16_bf16 v[80:95], v[216:219], v[124:127], v[80:95]
	s_waitcnt lgkmcnt(0)
	v_mfma_f32_32x32x16_bf16 v[64:79], v[220:223], v[124:127], v[64:79]
	v_mov_b32_e32 v149, v133
	v_mov_b32_e32 v150, v132
	v_mov_b32_e32 v151, v193
	s_nop 0
	v_lshlrev_b32_e32 v151, 2, v151
	v_sub_u32_e32 v154, v151, v149
	v_sub_u32_e32 v149, s12, v150
	v_add_u32_e32 v149, v149, v151
	v_and_b32_e32 v162, -16, v154
	v_add_u32_e32 v153, 0xe8, v149
	v_add_u32_e32 v149, 0x108, v149
	v_cmp_eq_u32_e32 vcc, s14, v162
	v_cmp_gt_u32_e64 s[12:13], 16, v154
	v_cndmask_b32_e32 v149, 0, v149, vcc
	v_lshl_add_u32 v149, v149, 2, 0
	v_add_u32_e32 v149, 0x18800, v149
	ds_read_b32 v152, v149
	v_mov_b32_e32 v149, 0xff800000
	v_mov_b32_e32 v150, 0xff800000
	s_and_saveexec_b64 s[14:15], s[12:13]
	s_cbranch_execz .LBB0_1044
	v_lshl_add_u32 v150, v153, 2, 0
	v_add_u32_e32 v150, 0x18800, v150
	ds_read_b32 v150, v150
	s_waitcnt lgkmcnt(0)
	v_add_f32_e32 v150, v80, v150

; #define ALAS __attribute__((address_space(3)))
; __device__ __forceinline__ void qkt(f32x16& p0, f32x16& p1, const ALAS char* Ks, const bf16x8* qr, int r32, int hi) {
;   p0 = f32x16{}; p1 = f32x16{};
; #pragma unroll
;   for (int d0 = 0; d0 < 8; ++d0) { int cb = (d0 * 16 + hi * 8) * 2;
;     bf16x8 b0 = *(const ALAS bf16x8*)(Ks + KSWZ(r32, cb));
;     bf16x8 b1 = *(const ALAS bf16x8*)(Ks + KSWZ(32 + r32, cb));
;     p0 = __builtin_amdgcn_mfma_f32_32x32x16_bf16(b0, qr[d0], p0, 0, 0, 0);
;     p1 = __builtin_amdgcn_mfma_f32_32x32x16_bf16(b1, qr[d0], p1, 0, 0, 0); }
; }
; template <int MODE> __device__ __forceinline__ void modify(f32x16& p0, f32x16& p1, const Mod& M, int j, float& boff) {
;     ...
;       const int base = (kr - M.rq + 7) * 31 + 15 - M.c + 4 * M.hi; const int d0 = 4 * M.hi - M.cs;
; #pragma unroll
;       for (int r = 0; r < 16; ++r) { const int cr = (r & 3) + 8 * (r >> 2);
;         const bool v0 = (unsigned)(cr + d0) < 16u, v1 = (unsigned)(cr + 32 + d0) < 16u;
;         const float b0 = M.tab[v0 ? base + cr : 0], b1 = M.tab[v1 ? base + cr + 32 : 0];
;         p0[r] = v0 ? p0[r] + b0 : NEG; p1[r] = v1 ? p1[r] + b1 : NEG; }
.LBB0_1697:
	s_add_i32 s8, s16, s47
	v_cmp_ge_i32_e32 vcc, s8, v139
	v_cmp_lt_i32_e64 s[6:7], s8, v141
	s_and_b64 s[6:7], vcc, s[6:7]
	s_andn2_b64 vcc, exec, s[6:7]
	s_cbranch_vccnz .LBB0_1736
	s_and_b32 s73, s16, 1
	v_mov_b32_e32 v64, v136
	v_mov_b32_e32 v65, v137
	s_lshl_b32 s6, s73, 14
	s_add_i32 s6, s6, 0
	s_add_i32 s6, s6, 0x10000
	v_lshlrev_b32_e32 v149, 4, v65
	v_lshlrev_b32_e32 v158, 4, v64
	v_and_b32_e32 v158, 0x70, v158
	v_lshl_add_u32 v159, v64, 8, s6
	v_xad_u32 v150, v149, v158, v159
	v_add_u32_e32 v247, 32, v149
	v_xad_u32 v151, v247, v158, v159
	v_add_u32_e32 v247, 64, v149
	v_xad_u32 v152, v247, v158, v159
	v_add_u32_e32 v247, 0x60, v149
	v_xad_u32 v153, v247, v158, v159
	s_sub_i32 s6, s8, s71
	s_mul_i32 s6, s6, 31
	s_movk_i32 s8, 0xffe0
	ds_read_b128 v[208:211], v150
	ds_read_b128 v[212:215], v150 offset:8192
	ds_read_b128 v[216:219], v151
	ds_read_b128 v[220:223], v151 offset:8192
	ds_read_b128 v[224:227], v152
	ds_read_b128 v[228:231], v152 offset:8192
	s_waitcnt lgkmcnt(5)
	v_mfma_f32_32x32x16_bf16 v[80:95], v[208:211], v[96:99], 0
	ds_read_b128 v[208:211], v153
	s_waitcnt lgkmcnt(5)
	v_mfma_f32_32x32x16_bf16 v[64:79], v[212:215], v[96:99], 0
	ds_read_b128 v[212:215], v153 offset:8192
	s_waitcnt lgkmcnt(5)
	v_mfma_f32_32x32x16_bf16 v[80:95], v[216:219], v[100:103], v[80:95]
	ds_read_b128 v[216:219], v150 offset:128
	s_waitcnt lgkmcnt(5)
	v_mfma_f32_32x32x16_bf16 v[64:79], v[220:223], v[100:103], v[64:79]
	ds_read_b128 v[220:223], v150 offset:8320
	s_waitcnt lgkmcnt(5)
	v_mfma_f32_32x32x16_bf16 v[80:95], v[224:227], v[104:107], v[80:95]
	ds_read_b128 v[224:227], v151 offset:128
	s_waitcnt lgkmcnt(5)
	v_mfma_f32_32x32x16_bf16 v[64:79], v[228:231], v[104:107], v[64:79]
	ds_read_b128 v[228:231], v151 offset:8320
	s_waitcnt lgkmcnt(5)
	v_mfma_f32_32x32x16_bf16 v[80:95], v[208:211], v[108:111], v[80:95]
	ds_read_b128 v[208:211], v152 offset:128
	s_waitcnt lgkmcnt(5)
	v_mfma_f32_32x32x16_bf16 v[64:79], v[212:215], v[108:111], v[64:79]
	ds_read_b128 v[212:215], v152 offset:8320
	s_waitcnt lgkmcnt(5)
	v_mfma_f32_32x32x16_bf16 v[80:95], v[216:219], v[112:115], v[80:95]
	ds_read_b128 v[216:219], v153 offset:128
	s_waitcnt lgkmcnt(5)
	v_mfma_f32_32x32x16_bf16 v[64:79], v[220:223], v[112:115], v[64:79]
	ds_read_b128 v[220:223], v153 offset:8320
	s_waitcnt lgkmcnt(5)
	v_mfma_f32_32x32x16_bf16 v[80:95], v[224:227], v[116:119], v[80:95]
	s_waitcnt lgkmcnt(4)
	v_mfma_f32_32x32x16_bf16 v[64:79], v[228:231], v[116:119], v[64:79]
	s_waitcnt lgkmcnt(3)
	v_mfma_f32_32x32x16_bf16 v[80:95], v[208:211], v[120:123], v[80:95]
	s_waitcnt lgkmcnt(2)
	v_mfma_f32_32x32x16_bf16 v[64:79], v[212:215], v[120:123], v[64:79]
	s_waitcnt lgkmcnt(1)
	v_mfma_f32_32x32x16_bf16 v[80:95], v[216:219], v[124:127], v[80:95]
	s_waitcnt lgkmcnt(0)
	v_mfma_f32_32x32x16_bf16 v[64:79], v[220:223], v[124:127], v[64:79]
	v_mov_b32_e32 v149, v193
	v_mov_b32_e32 v150, v133
	v_mov_b32_e32 v151, v132
	s_nop 0
	v_lshlrev_b32_e32 v149, 2, v149
	v_sub_u32_e32 v155, v149, v150
	v_sub_u32_e32 v150, s6, v151
	v_add_u32_e32 v149, v150, v149
	v_and_b32_e32 v162, -16, v155
	v_add_u32_e32 v154, 0xe8, v149
	v_add_u32_e32 v149, 0x108, v149
	v_cmp_eq_u32_e32 vcc, s8, v162
	v_cmp_gt_u32_e64 s[6:7], 16, v155
	v_cndmask_b32_e32 v149, 0, v149, vcc
	v_lshl_add_u32 v149, v149, 2, 0
	v_add_u32_e32 v149, 0x18800, v149
	ds_read_b32 v152, v149
	v_mov_b32_e32 v149, 0xff800000
	v_mov_b32_e32 v150, 0xff800000
	s_and_saveexec_b64 s[8:9], s[6:7]
	s_cbranch_execz .LBB0_1700
	v_lshl_add_u32 v150, v154, 2, 0
	v_add_u32_e32 v150, 0x18800, v150
	ds_read_b32 v150, v150
	s_waitcnt lgkmcnt(0)
	v_add_f32_e32 v150, v80, v150
